# grid barriers: XCD leaders post to the top counter without waiting for the return; all workgroups poll that counter directly (one memory round trip fewer per barrier)
# speedup vs baseline: 1.0027x; 1.0027x over previous
; __device__ __forceinline__ void fast_grid_barrier(unsigned* base, int seam, int tid) {
;     asm volatile("s_waitcnt vmcnt(0)" ::: "memory");
;     __syncthreads();
;     if (tid == 0) {
;         unsigned* cnt = base + seam * 128;
;         unsigned* flg = cnt + 64;
;         __builtin_amdgcn_fence(__ATOMIC_RELEASE, "agent");
;         asm volatile("s_waitcnt vmcnt(0)" ::: "memory");
;         const unsigned old = __hip_atomic_fetch_add(cnt, 1u, __ATOMIC_RELAXED, __HIP_MEMORY_SCOPE_AGENT);
;         if (old == gridDim.x - 1) __hip_atomic_store(flg, 1u, __ATOMIC_RELAXED, __HIP_MEMORY_SCOPE_AGENT);
;         else { unsigned sp = 0; while (__hip_atomic_load(flg, __ATOMIC_RELAXED, __HIP_MEMORY_SCOPE_AGENT) == 0u) { __builtin_amdgcn_s_sleep(2); if (++sp > (1u << 22)) break; } }
;         __builtin_amdgcn_fence(__ATOMIC_ACQUIRE, "agent");
;         asm volatile("s_waitcnt vmcnt(0)" ::: "memory");
;     }
;     __syncthreads();
.LBB0_84:
	s_cmp_lt_i32 s47, 3
	s_cbranch_scc1 .LBB0_101
	s_waitcnt vmcnt(0)
	v_cmp_eq_u32_e32 vcc, 0, v202
	s_barrier
	s_and_saveexec_b64 s[0:1], vcc
	s_cbranch_execz .LBB0_100
	s_load_dwordx2 s[4:5], s[84:85], 0x90
	s_lshl_b32 s3, s98, 6
	v_mov_b32_e32 v0, s3
	v_mov_b32_e32 v2, 1
	s_waitcnt lgkmcnt(0)
	s_add_u32 s4, s4, 0x1400
	s_addc_u32 s5, s5, 0
	s_lshl_b32 s6, s98, 2
	v_mov_b32_e32 v1, s6
	v_mov_b32_e32 v2, 0
	global_load_dword v1, v1, s[4:5] sc1
	global_load_dword v2, v2, s[4:5] offset:64 sc1
	s_waitcnt vmcnt(0)
	v_readfirstlane_b32 s99, v1
	v_readfirstlane_b32 s100, v2
	v_mov_b32_e32 v2, 1
	s_nop 3
	global_atomic_add v1, v0, v2, s[4:5] offset:128 sc0
	s_mul_i32 s6, s99, 1
	s_add_i32 s3, s6, -1
	s_lshl_b32 s6, s98, 6
	s_sub_u32 s6, s4, s6
	s_subb_u32 s7, s5, 0
	s_mul_i32 s4, s100, 1
	s_waitcnt vmcnt(0)
	v_cmp_ne_u32_e32 vcc, s3, v1
	s_cbranch_vccnz .Lsm1_wtop
	buffer_wbl2 sc1
	s_waitcnt vmcnt(0)
	global_atomic_add v0, v2, s[6:7] offset:2176

; __device__ __forceinline__ void fast_grid_barrier(unsigned* base, int seam, int tid) {
;     asm volatile("s_waitcnt vmcnt(0)" ::: "memory");
;     __syncthreads();
;     if (tid == 0) {
;         unsigned* cnt = base + seam * 128;
;         unsigned* flg = cnt + 64;
;         __builtin_amdgcn_fence(__ATOMIC_RELEASE, "agent");
;         asm volatile("s_waitcnt vmcnt(0)" ::: "memory");
;         const unsigned old = __hip_atomic_fetch_add(cnt, 1u, __ATOMIC_RELAXED, __HIP_MEMORY_SCOPE_AGENT);
;         if (old == gridDim.x - 1) __hip_atomic_store(flg, 1u, __ATOMIC_RELAXED, __HIP_MEMORY_SCOPE_AGENT);
;         else { unsigned sp = 0; while (__hip_atomic_load(flg, __ATOMIC_RELAXED, __HIP_MEMORY_SCOPE_AGENT) == 0u) { __builtin_amdgcn_s_sleep(2); if (++sp > (1u << 22)) break; } }
;         __builtin_amdgcn_fence(__ATOMIC_ACQUIRE, "agent");
;         asm volatile("s_waitcnt vmcnt(0)" ::: "memory");
;     }
;     __syncthreads();
.Lsm1_wtop_loop:
	global_load_dword v1, v0, s[6:7] offset:2176 sc1
	s_waitcnt vmcnt(0)
	v_cmp_le_u32_e32 vcc, s4, v1
	s_cbranch_vccnz .Lsm1_topdone
	s_sleep 1
	s_add_i32 s3, s3, -1
	s_cmp_lg_u32 s3, 0
	s_cbranch_scc1 .Lsm1_wtop_loop

; __device__ __forceinline__ void fast_grid_barrier(unsigned* base, int seam, int tid) {
;     asm volatile("s_waitcnt vmcnt(0)" ::: "memory");
;     __syncthreads();
;     if (tid == 0) {
;         unsigned* cnt = base + seam * 128;
;         unsigned* flg = cnt + 64;
;         __builtin_amdgcn_fence(__ATOMIC_RELEASE, "agent");
;         asm volatile("s_waitcnt vmcnt(0)" ::: "memory");
;         const unsigned old = __hip_atomic_fetch_add(cnt, 1u, __ATOMIC_RELAXED, __HIP_MEMORY_SCOPE_AGENT);
;         if (old == gridDim.x - 1) __hip_atomic_store(flg, 1u, __ATOMIC_RELAXED, __HIP_MEMORY_SCOPE_AGENT);
;         else { unsigned sp = 0; while (__hip_atomic_load(flg, __ATOMIC_RELAXED, __HIP_MEMORY_SCOPE_AGENT) == 0u) { __builtin_amdgcn_s_sleep(2); if (++sp > (1u << 22)) break; } }
;         __builtin_amdgcn_fence(__ATOMIC_ACQUIRE, "agent");
;         asm volatile("s_waitcnt vmcnt(0)" ::: "memory");
;     }
;     __syncthreads();
.LBB0_167:
	s_waitcnt vmcnt(0)
	v_cmp_eq_u32_e32 vcc, 0, v202
	s_waitcnt vmcnt(0) lgkmcnt(0)
	s_barrier
	s_and_saveexec_b64 s[0:1], vcc
	s_cbranch_execz .LBB0_182
	s_load_dwordx2 s[4:5], s[84:85], 0x90
	s_lshl_b32 s3, s98, 6
	v_mov_b32_e32 v0, s3
	v_mov_b32_e32 v2, 1
	s_waitcnt lgkmcnt(0)
	s_add_u32 s4, s4, 0x1400
	s_addc_u32 s5, s5, 0
	global_atomic_add v1, v0, v2, s[4:5] offset:128 sc0
	s_mul_i32 s6, s99, 2
	s_add_i32 s3, s6, -1
	s_lshl_b32 s6, s98, 6
	s_sub_u32 s6, s4, s6
	s_subb_u32 s7, s5, 0
	s_mul_i32 s4, s100, 2
	s_waitcnt vmcnt(0)
	v_cmp_ne_u32_e32 vcc, s3, v1
	s_cbranch_vccnz .Lsm2_wtop
	buffer_wbl2 sc1
	s_waitcnt vmcnt(0)
	global_atomic_add v0, v2, s[6:7] offset:2176

; __device__ __forceinline__ void fast_grid_barrier(unsigned* base, int seam, int tid) {
;     asm volatile("s_waitcnt vmcnt(0)" ::: "memory");
;     __syncthreads();
;     if (tid == 0) {
;         unsigned* cnt = base + seam * 128;
;         unsigned* flg = cnt + 64;
;         __builtin_amdgcn_fence(__ATOMIC_RELEASE, "agent");
;         asm volatile("s_waitcnt vmcnt(0)" ::: "memory");
;         const unsigned old = __hip_atomic_fetch_add(cnt, 1u, __ATOMIC_RELAXED, __HIP_MEMORY_SCOPE_AGENT);
;         if (old == gridDim.x - 1) __hip_atomic_store(flg, 1u, __ATOMIC_RELAXED, __HIP_MEMORY_SCOPE_AGENT);
;         else { unsigned sp = 0; while (__hip_atomic_load(flg, __ATOMIC_RELAXED, __HIP_MEMORY_SCOPE_AGENT) == 0u) { __builtin_amdgcn_s_sleep(2); if (++sp > (1u << 22)) break; } }
;         __builtin_amdgcn_fence(__ATOMIC_ACQUIRE, "agent");
;         asm volatile("s_waitcnt vmcnt(0)" ::: "memory");
;     }
;     __syncthreads();
.LBB0_544:
	s_waitcnt lgkmcnt(0)
	s_cmp_lt_i32 s47, 5
	s_cbranch_scc1 .LBB0_561
	s_waitcnt vmcnt(0)
	s_waitcnt vmcnt(0)
	s_barrier
	s_mov_b64 s[0:1], exec
	v_readlane_b32 s4, v249, 28
	v_readlane_b32 s5, v249, 29
	s_and_b64 s[4:5], s[0:1], s[4:5]
	s_mov_b64 exec, s[4:5]
	s_cbranch_execz .LBB0_560
	s_load_dwordx2 s[4:5], s[84:85], 0x90
	s_lshl_b32 s3, s98, 6
	v_mov_b32_e32 v0, s3
	v_mov_b32_e32 v2, 1
	s_waitcnt lgkmcnt(0)
	s_add_u32 s4, s4, 0x1400
	s_addc_u32 s5, s5, 0
	global_atomic_add v1, v0, v2, s[4:5] offset:128 sc0
	s_mul_i32 s6, s99, 3
	s_add_i32 s3, s6, -1
	s_lshl_b32 s6, s98, 6
	s_sub_u32 s6, s4, s6
	s_subb_u32 s7, s5, 0
	s_mul_i32 s4, s100, 3
	s_waitcnt vmcnt(0)
	v_cmp_ne_u32_e32 vcc, s3, v1
	s_cbranch_vccnz .Lsm3_wtop
	buffer_wbl2 sc1
	s_waitcnt vmcnt(0)
	global_atomic_add v0, v2, s[6:7] offset:2176

; __device__ __forceinline__ void fast_grid_barrier(unsigned* base, int seam, int tid) {
;     asm volatile("s_waitcnt vmcnt(0)" ::: "memory");
;     __syncthreads();
;     if (tid == 0) {
;         unsigned* cnt = base + seam * 128;
;         unsigned* flg = cnt + 64;
;         __builtin_amdgcn_fence(__ATOMIC_RELEASE, "agent");
;         asm volatile("s_waitcnt vmcnt(0)" ::: "memory");
;         const unsigned old = __hip_atomic_fetch_add(cnt, 1u, __ATOMIC_RELAXED, __HIP_MEMORY_SCOPE_AGENT);
;         if (old == gridDim.x - 1) __hip_atomic_store(flg, 1u, __ATOMIC_RELAXED, __HIP_MEMORY_SCOPE_AGENT);
;         else { unsigned sp = 0; while (__hip_atomic_load(flg, __ATOMIC_RELAXED, __HIP_MEMORY_SCOPE_AGENT) == 0u) { __builtin_amdgcn_s_sleep(2); if (++sp > (1u << 22)) break; } }
;         __builtin_amdgcn_fence(__ATOMIC_ACQUIRE, "agent");
;         asm volatile("s_waitcnt vmcnt(0)" ::: "memory");
;     }
;     __syncthreads();
.LBB0_586:
	s_waitcnt lgkmcnt(0)
	s_cmp_lt_i32 s47, 6
	s_cbranch_scc1 .LBB0_603
	s_waitcnt vmcnt(0)
	v_cmp_eq_u32_e32 vcc, 0, v202
	s_barrier
	s_and_saveexec_b64 s[0:1], vcc
	s_cbranch_execz .LBB0_602
	s_load_dwordx2 s[4:5], s[84:85], 0x90
	s_lshl_b32 s3, s98, 6
	v_mov_b32_e32 v0, s3
	v_mov_b32_e32 v2, 1
	s_waitcnt lgkmcnt(0)
	s_add_u32 s4, s4, 0x1400
	s_addc_u32 s5, s5, 0
	global_atomic_add v1, v0, v2, s[4:5] offset:128 sc0
	s_mul_i32 s6, s99, 4
	s_add_i32 s3, s6, -1
	s_lshl_b32 s6, s98, 6
	s_sub_u32 s6, s4, s6
	s_subb_u32 s7, s5, 0
	s_mul_i32 s4, s100, 4
	s_waitcnt vmcnt(0)
	v_cmp_ne_u32_e32 vcc, s3, v1
	s_cbranch_vccnz .Lsm4_wtop
	buffer_wbl2 sc1
	s_waitcnt vmcnt(0)
	global_atomic_add v0, v2, s[6:7] offset:2176

; __device__ __forceinline__ void fast_grid_barrier(unsigned* base, int seam, int tid) {
;     asm volatile("s_waitcnt vmcnt(0)" ::: "memory");
;     __syncthreads();
;     if (tid == 0) {
;         unsigned* cnt = base + seam * 128;
;         unsigned* flg = cnt + 64;
;         __builtin_amdgcn_fence(__ATOMIC_RELEASE, "agent");
;         asm volatile("s_waitcnt vmcnt(0)" ::: "memory");
;         const unsigned old = __hip_atomic_fetch_add(cnt, 1u, __ATOMIC_RELAXED, __HIP_MEMORY_SCOPE_AGENT);
;         if (old == gridDim.x - 1) __hip_atomic_store(flg, 1u, __ATOMIC_RELAXED, __HIP_MEMORY_SCOPE_AGENT);
;         else { unsigned sp = 0; while (__hip_atomic_load(flg, __ATOMIC_RELAXED, __HIP_MEMORY_SCOPE_AGENT) == 0u) { __builtin_amdgcn_s_sleep(2); if (++sp > (1u << 22)) break; } }
;         __builtin_amdgcn_fence(__ATOMIC_ACQUIRE, "agent");
;         asm volatile("s_waitcnt vmcnt(0)" ::: "memory");
;     }
;     __syncthreads();
.LBB0_609:
	s_cmp_lt_i32 s47, 7
	s_cbranch_scc1 .LBB0_626
	s_waitcnt vmcnt(0)
	v_cmp_eq_u32_e32 vcc, 0, v202
	s_waitcnt vmcnt(0) lgkmcnt(0)
	s_barrier
	s_and_saveexec_b64 s[0:1], vcc
	s_cbranch_execz .LBB0_625
	s_load_dwordx2 s[4:5], s[84:85], 0x90
	s_lshl_b32 s3, s98, 6
	v_mov_b32_e32 v0, s3
	v_mov_b32_e32 v2, 1
	s_waitcnt lgkmcnt(0)
	s_add_u32 s4, s4, 0x1400
	s_addc_u32 s5, s5, 0
	global_atomic_add v1, v0, v2, s[4:5] offset:128 sc0
	s_mul_i32 s6, s99, 5
	s_add_i32 s3, s6, -1
	s_lshl_b32 s6, s98, 6
	s_sub_u32 s6, s4, s6
	s_subb_u32 s7, s5, 0
	s_mul_i32 s4, s100, 5
	s_waitcnt vmcnt(0)
	v_cmp_ne_u32_e32 vcc, s3, v1
	s_cbranch_vccnz .Lsm5_wtop
	buffer_wbl2 sc1
	s_waitcnt vmcnt(0)
	global_atomic_add v0, v2, s[6:7] offset:2176

; __device__ __forceinline__ void fast_grid_barrier(unsigned* base, int seam, int tid) {
;     asm volatile("s_waitcnt vmcnt(0)" ::: "memory");
;     __syncthreads();
;     if (tid == 0) {
;         unsigned* cnt = base + seam * 128;
;         unsigned* flg = cnt + 64;
;         __builtin_amdgcn_fence(__ATOMIC_RELEASE, "agent");
;         asm volatile("s_waitcnt vmcnt(0)" ::: "memory");
;         const unsigned old = __hip_atomic_fetch_add(cnt, 1u, __ATOMIC_RELAXED, __HIP_MEMORY_SCOPE_AGENT);
;         if (old == gridDim.x - 1) __hip_atomic_store(flg, 1u, __ATOMIC_RELAXED, __HIP_MEMORY_SCOPE_AGENT);
;         else { unsigned sp = 0; while (__hip_atomic_load(flg, __ATOMIC_RELAXED, __HIP_MEMORY_SCOPE_AGENT) == 0u) { __builtin_amdgcn_s_sleep(2); if (++sp > (1u << 22)) break; } }
;         __builtin_amdgcn_fence(__ATOMIC_ACQUIRE, "agent");
;         asm volatile("s_waitcnt vmcnt(0)" ::: "memory");
;     }
;     __syncthreads();
.LBB0_692:
	s_waitcnt vmcnt(0)
	v_cmp_eq_u32_e32 vcc, 0, v202
	s_waitcnt vmcnt(0) lgkmcnt(0)
	s_barrier
	s_and_saveexec_b64 s[0:1], vcc
	s_cbranch_execz .LBB0_707
	s_load_dwordx2 s[4:5], s[84:85], 0x90
	s_lshl_b32 s3, s98, 6
	v_mov_b32_e32 v0, s3
	v_mov_b32_e32 v2, 1
	s_waitcnt lgkmcnt(0)
	s_add_u32 s4, s4, 0x1400
	s_addc_u32 s5, s5, 0
	global_atomic_add v1, v0, v2, s[4:5] offset:128 sc0
	s_mul_i32 s6, s99, 6
	s_add_i32 s3, s6, -1
	s_lshl_b32 s6, s98, 6
	s_sub_u32 s6, s4, s6
	s_subb_u32 s7, s5, 0
	s_mul_i32 s4, s100, 6
	s_waitcnt vmcnt(0)
	v_cmp_ne_u32_e32 vcc, s3, v1
	s_cbranch_vccnz .Lsm6_wtop
	buffer_wbl2 sc1
	s_waitcnt vmcnt(0)
	global_atomic_add v0, v2, s[6:7] offset:2176

; __device__ __forceinline__ void fast_grid_barrier(unsigned* base, int seam, int tid) {
;     asm volatile("s_waitcnt vmcnt(0)" ::: "memory");
;     __syncthreads();
;     if (tid == 0) {
;         unsigned* cnt = base + seam * 128;
;         unsigned* flg = cnt + 64;
;         __builtin_amdgcn_fence(__ATOMIC_RELEASE, "agent");
;         asm volatile("s_waitcnt vmcnt(0)" ::: "memory");
;         const unsigned old = __hip_atomic_fetch_add(cnt, 1u, __ATOMIC_RELAXED, __HIP_MEMORY_SCOPE_AGENT);
;         if (old == gridDim.x - 1) __hip_atomic_store(flg, 1u, __ATOMIC_RELAXED, __HIP_MEMORY_SCOPE_AGENT);
;         else { unsigned sp = 0; while (__hip_atomic_load(flg, __ATOMIC_RELAXED, __HIP_MEMORY_SCOPE_AGENT) == 0u) { __builtin_amdgcn_s_sleep(2); if (++sp > (1u << 22)) break; } }
;         __builtin_amdgcn_fence(__ATOMIC_ACQUIRE, "agent");
;         asm volatile("s_waitcnt vmcnt(0)" ::: "memory");
;     }
;     __syncthreads();
.LBB0_1069:
	s_waitcnt lgkmcnt(0)
	s_cmp_lt_i32 s47, 9
	s_cbranch_scc1 .LBB0_1086
	s_waitcnt vmcnt(0)
	s_barrier
	s_mov_b64 s[0:1], exec
	v_readlane_b32 s4, v249, 8
	v_readlane_b32 s5, v249, 9
	s_and_b64 s[4:5], s[0:1], s[4:5]
	s_mov_b64 exec, s[4:5]
	s_cbranch_execz .LBB0_1085
	s_load_dwordx2 s[4:5], s[84:85], 0x90
	s_lshl_b32 s3, s98, 6
	v_mov_b32_e32 v0, s3
	v_mov_b32_e32 v2, 1
	s_waitcnt lgkmcnt(0)
	s_add_u32 s4, s4, 0x1400
	s_addc_u32 s5, s5, 0
	global_atomic_add v1, v0, v2, s[4:5] offset:128 sc0
	s_mul_i32 s6, s99, 7
	s_add_i32 s3, s6, -1
	s_lshl_b32 s6, s98, 6
	s_sub_u32 s6, s4, s6
	s_subb_u32 s7, s5, 0
	s_mul_i32 s4, s100, 7
	s_waitcnt vmcnt(0)
	v_cmp_ne_u32_e32 vcc, s3, v1
	s_cbranch_vccnz .Lsm7_wtop
	buffer_wbl2 sc1
	s_waitcnt vmcnt(0)
	global_atomic_add v0, v2, s[6:7] offset:2176
